# lever 1/2 extended: mem-attention first (peeled) tile PV section de-serialised with the same fragment ring
# baseline (speedup 1.0000x reference)
.LBB0_912:
	s_or_b64 exec, exec, s[40:41]
	v_mad_u32_u24 v0, v152, s51, 0
	v_lshlrev_b32_e32 v193, 4, v178
	v_add_u32_e32 v189, v0, v193
	ds_read_b128 v[0:3], v189
	ds_read_b128 v[34:37], v189 offset:32
	ds_read_b128 v[16:19], v189 offset:8704
	ds_read_b128 v[38:41], v189 offset:8736
	v_lshlrev_b32_e32 v191, 4, v144
	s_waitcnt lgkmcnt(3)
	v_mfma_f32_32x32x16_bf16 v[0:15], v[0:3], v[124:127], 0
	s_waitcnt lgkmcnt(1)
	v_mfma_f32_32x32x16_bf16 v[16:31], v[16:19], v[124:127], 0
	v_mfma_f32_32x32x16_bf16 v[0:15], v[34:37], v[120:123], v[0:15]
	s_waitcnt lgkmcnt(0)
	v_mfma_f32_32x32x16_bf16 v[16:31], v[38:41], v[120:123], v[16:31]
	ds_read_b128 v[34:37], v189 offset:64
	ds_read_b128 v[38:41], v189 offset:96
	s_waitcnt lgkmcnt(1)
	v_mfma_f32_32x32x16_bf16 v[0:15], v[34:37], v[116:119], v[0:15]
	ds_read_b128 v[34:37], v189 offset:8768
	ds_read_b128 v[42:45], v189 offset:8800
	s_waitcnt lgkmcnt(1)
	v_mfma_f32_32x32x16_bf16 v[16:31], v[34:37], v[116:119], v[16:31]
	v_mfma_f32_32x32x16_bf16 v[0:15], v[38:41], v[112:115], v[0:15]
	ds_read_b128 v[34:37], v189 offset:128
	ds_read_b128 v[38:41], v189 offset:160
	s_waitcnt lgkmcnt(2)
	v_mfma_f32_32x32x16_bf16 v[16:31], v[42:45], v[112:115], v[16:31]
	s_waitcnt lgkmcnt(1)
	v_mfma_f32_32x32x16_bf16 v[0:15], v[34:37], v[108:111], v[0:15]
	ds_read_b128 v[34:37], v189 offset:8832
	ds_read_b128 v[42:45], v189 offset:8864
	s_waitcnt lgkmcnt(1)
	v_mfma_f32_32x32x16_bf16 v[16:31], v[34:37], v[108:111], v[16:31]
	v_mfma_f32_32x32x16_bf16 v[0:15], v[38:41], v[104:107], v[0:15]
	ds_read_b128 v[34:37], v189 offset:192
	ds_read_b128 v[38:41], v189 offset:224
	s_waitcnt lgkmcnt(2)
	v_mfma_f32_32x32x16_bf16 v[16:31], v[42:45], v[104:107], v[16:31]
	s_waitcnt lgkmcnt(1)
	v_mfma_f32_32x32x16_bf16 v[0:15], v[34:37], v[100:103], v[0:15]
	ds_read_b128 v[34:37], v189 offset:8896
	ds_read_b128 v[42:45], v189 offset:8928
	s_waitcnt lgkmcnt(1)
	v_mfma_f32_32x32x16_bf16 v[16:31], v[34:37], v[100:103], v[16:31]
	s_waitcnt lgkmcnt(0)
	v_mfma_f32_32x32x16_bf16 v[16:31], v[42:45], v[96:99], v[16:31]
	v_mfma_f32_32x32x16_bf16 v[0:15], v[38:41], v[96:99], v[0:15]
	s_nop 10
	v_max_f32_e32 v33, v16, v16
	v_max_f32_e32 v34, v0, v0
	v_max_f32_e32 v33, v34, v33
	v_max_f32_e32 v34, v17, v17
	v_max_f32_e32 v35, v1, v1
	v_max_f32_e32 v34, v35, v34
	v_max_f32_e32 v35, v19, v19
	v_max_f32_e32 v36, v3, v3
	v_max_f32_e32 v35, v36, v35
	v_max3_f32 v36, v2, v18, v6
	v_max3_f32 v35, v35, v7, v23
	v_max3_f32 v33, v33, v4, v20
	v_max3_f32 v34, v34, v5, v21
	v_max3_f32 v36, v36, v22, v10
	v_max3_f32 v35, v35, v11, v27
	v_max3_f32 v33, v33, v8, v24
	v_max3_f32 v34, v34, v9, v25
	v_max3_f32 v36, v36, v26, v14
	v_max3_f32 v35, v35, v15, v31
	v_max3_f32 v33, v33, v12, v28
	v_max3_f32 v34, v34, v13, v29
	v_max3_f32 v35, v36, v30, v35
	v_max3_f32 v33, v33, v34, v35
	v_mov_b32_e32 v34, v33
	s_nop 1
	v_permlane32_swap_b32_e32 v33, v34
	v_max_f32_e32 v34, v34, v34
	v_max_f32_e32 v33, v33, v33
	v_max_f32_e32 v194, v33, v34
	v_mul_u32_u24_e32 v34, 0x88, v152
	v_add3_u32 v179, 0, v32, v34
	v_sub_f32_e32 v8, v8, v194
	v_sub_f32_e32 v0, v0, v194
	v_sub_f32_e32 v1, v1, v194
	v_sub_f32_e32 v2, v2, v194
	v_sub_f32_e32 v3, v3, v194
	v_exp_f32_e32 v159, v8
	v_add_u32_e32 v8, 0x8800, v179
	v_exp_f32_e32 v163, v0
	v_exp_f32_e32 v149, v1
	v_exp_f32_e32 v162, v2
	v_exp_f32_e32 v148, v3
	ds_read2_b64 v[0:3], v8 offset1:2
	v_exp_f32_e64 v33, -v194
	v_sub_f32_e32 v4, v4, v194
	v_sub_f32_e32 v5, v5, v194
	v_sub_f32_e32 v6, v6, v194
	v_sub_f32_e32 v7, v7, v194
	v_exp_f32_e32 v161, v4
	v_exp_f32_e32 v143, v5
	v_exp_f32_e32 v160, v6
	v_exp_f32_e32 v142, v7
	v_mul_f32_e32 v64, 0, v33
	v_mov_b32_e32 v65, v64
	v_mov_b32_e32 v66, v64
	v_mov_b32_e32 v67, v64
	v_mov_b32_e32 v68, v64
	v_mov_b32_e32 v69, v64
	v_mov_b32_e32 v70, v64
	v_mov_b32_e32 v71, v64
	v_mov_b32_e32 v72, v64
	v_mov_b32_e32 v73, v64
	v_mov_b32_e32 v74, v64
	v_mov_b32_e32 v75, v64
	v_mov_b32_e32 v76, v64
	v_mov_b32_e32 v77, v64
	v_mov_b32_e32 v78, v64
	v_mov_b32_e32 v79, v64
	v_cvt_pk_bf16_f32 v196, v163, v149
	v_cvt_pk_bf16_f32 v197, v162, v148
	v_cvt_pk_bf16_f32 v198, v161, v143
	v_cvt_pk_bf16_f32 v199, v160, v142
	ds_read2_b64 v[4:7], v8 offset0:4 offset1:6
	v_sub_f32_e32 v9, v9, v194
	s_waitcnt lgkmcnt(1)
	v_mfma_f32_32x32x16_bf16 v[48:63], v[0:3], v[196:199], v[64:79]
	v_sub_f32_e32 v10, v10, v194
	v_sub_f32_e32 v11, v11, v194
	v_sub_f32_e32 v12, v12, v194
	v_sub_f32_e32 v13, v13, v194
	v_sub_f32_e32 v14, v14, v194
	v_sub_f32_e32 v15, v15, v194
	v_exp_f32_e32 v141, v9
	v_exp_f32_e32 v158, v10
	v_exp_f32_e32 v140, v11
	v_exp_f32_e32 v173, v12
	v_exp_f32_e32 v171, v13
	v_exp_f32_e32 v172, v14
	v_exp_f32_e32 v170, v15
	v_cvt_pk_bf16_f32 v200, v159, v141
	v_cvt_pk_bf16_f32 v201, v158, v140
	v_cvt_pk_bf16_f32 v202, v173, v171
	v_cvt_pk_bf16_f32 v203, v172, v170
	ds_read2_b64 v[0:3], v8 offset0:8 offset1:10
	v_sub_f32_e32 v16, v16, v194
	s_waitcnt lgkmcnt(1)
	v_mfma_f32_32x32x16_bf16 v[48:63], v[4:7], v[200:203], v[48:63]
	v_sub_f32_e32 v17, v17, v194
	v_sub_f32_e32 v18, v18, v194
	v_sub_f32_e32 v19, v19, v194
	v_sub_f32_e32 v20, v20, v194
	v_sub_f32_e32 v21, v21, v194
	v_sub_f32_e32 v22, v22, v194
	v_sub_f32_e32 v23, v23, v194
	v_exp_f32_e32 v169, v16
	v_exp_f32_e32 v157, v17
	v_exp_f32_e32 v168, v18
	v_exp_f32_e32 v156, v19
	v_exp_f32_e32 v167, v20
	v_exp_f32_e32 v155, v21
	v_exp_f32_e32 v166, v22
	v_exp_f32_e32 v154, v23
	v_cvt_pk_bf16_f32 v204, v169, v157
	v_cvt_pk_bf16_f32 v205, v168, v156
	v_cvt_pk_bf16_f32 v206, v167, v155
	v_cvt_pk_bf16_f32 v207, v166, v154
	ds_read2_b64 v[4:7], v8 offset0:12 offset1:14
	v_sub_f32_e32 v24, v24, v194
	s_waitcnt lgkmcnt(1)
	v_mfma_f32_32x32x16_bf16 v[48:63], v[0:3], v[204:207], v[48:63]
	v_sub_f32_e32 v25, v25, v194
	v_sub_f32_e32 v26, v26, v194
	v_sub_f32_e32 v27, v27, v194
	v_sub_f32_e32 v28, v28, v194
	v_sub_f32_e32 v29, v29, v194
	v_sub_f32_e32 v30, v30, v194
	v_sub_f32_e32 v31, v31, v194
	v_exp_f32_e32 v165, v24
	v_exp_f32_e32 v151, v25
	v_exp_f32_e32 v164, v26
	v_exp_f32_e32 v150, v27
	v_exp_f32_e32 v175, v28
	v_exp_f32_e32 v177, v29
	v_exp_f32_e32 v174, v30
	v_exp_f32_e32 v176, v31
	v_cvt_pk_bf16_f32 v208, v165, v151
	v_cvt_pk_bf16_f32 v209, v164, v150
	v_cvt_pk_bf16_f32 v210, v175, v177
	v_cvt_pk_bf16_f32 v211, v174, v176
	v_add_u32_e32 v190, 0xb800, v179
	v_add_u32_e32 v241, 0x9800, v179
	v_add_u32_e32 v242, 0xa800, v179
	ds_read2_b64 v[216:219], v241 offset0:32 offset1:34
	ds_read2_b64 v[220:223], v241 offset0:36 offset1:38
	ds_read2_b64 v[224:227], v241 offset0:40 offset1:42
	ds_read2_b64 v[228:231], v241 offset0:44 offset1:46
	ds_read2_b64 v[232:235], v242 offset0:64 offset1:66
	ds_read2_b64 v[236:239], v242 offset0:68 offset1:70
	s_waitcnt lgkmcnt(6)
	v_mfma_f32_32x32x16_bf16 v[48:63], v[4:7], v[208:211], v[48:63]
	global_load_dwordx4 v[84:87], v[80:81], off offset:128
	s_nop 0
	global_load_dwordx4 v[80:83], v[82:83], off offset:128
	s_waitcnt lgkmcnt(5)
	v_mfma_f32_32x32x16_bf16 v[32:47], v[216:219], v[196:199], v[64:79]
	ds_read2_b64 v[216:219], v242 offset0:72 offset1:74
	s_waitcnt lgkmcnt(5)
	v_mfma_f32_32x32x16_bf16 v[32:47], v[220:223], v[200:203], v[32:47]
	ds_read2_b64 v[220:223], v242 offset0:76 offset1:78
	s_waitcnt lgkmcnt(5)
	v_mfma_f32_32x32x16_bf16 v[32:47], v[224:227], v[204:207], v[32:47]
	ds_read2_b64 v[224:227], v190 offset0:96 offset1:98
	s_waitcnt lgkmcnt(5)
	v_mfma_f32_32x32x16_bf16 v[32:47], v[228:231], v[208:211], v[32:47]
	ds_read2_b64 v[228:231], v190 offset0:100 offset1:102
	s_waitcnt lgkmcnt(5)
	v_mfma_f32_32x32x16_bf16 v[16:31], v[232:235], v[196:199], v[64:79]
	ds_read2_b64 v[232:235], v190 offset0:104 offset1:106
	s_waitcnt lgkmcnt(5)
	v_mfma_f32_32x32x16_bf16 v[16:31], v[236:239], v[200:203], v[16:31]
	ds_read2_b64 v[236:239], v190 offset0:108 offset1:110
	s_waitcnt lgkmcnt(5)
	v_mfma_f32_32x32x16_bf16 v[16:31], v[216:219], v[204:207], v[16:31]
	s_waitcnt lgkmcnt(4)
	v_mfma_f32_32x32x16_bf16 v[16:31], v[220:223], v[208:211], v[16:31]
	v_mov_b64_e32 v[0:1], v[64:65]
	v_mov_b64_e32 v[2:3], v[66:67]
	v_mov_b64_e32 v[4:5], v[68:69]
	v_mov_b64_e32 v[6:7], v[70:71]
	v_mov_b64_e32 v[8:9], v[72:73]
	v_mov_b64_e32 v[10:11], v[74:75]
	v_mov_b64_e32 v[12:13], v[76:77]
	v_mov_b64_e32 v[14:15], v[78:79]
	v_mul_lo_u32 v190, v136, s51
	s_nop 0
	s_waitcnt lgkmcnt(3)
	v_mfma_f32_32x32x16_bf16 v[0:15], v[224:227], v[196:199], v[0:15]
	s_waitcnt lgkmcnt(2)
	v_mfma_f32_32x32x16_bf16 v[0:15], v[228:231], v[200:203], v[0:15]
	s_waitcnt lgkmcnt(1)
	v_mfma_f32_32x32x16_bf16 v[0:15], v[232:235], v[204:207], v[0:15]
	s_waitcnt lgkmcnt(0)
	v_mfma_f32_32x32x16_bf16 v[0:15], v[236:239], v[208:211], v[0:15]
	s_and_saveexec_b64 s[38:39], s[6:7]
	s_cbranch_execz .LBB0_914
	v_add3_u32 v65, 0, v190, v191
	s_waitcnt vmcnt(2)
	ds_write_b128 v65, v[128:131] offset:17408
